# P0 MOD: two per-wave prefetch loads touching the wave's 128 w_ada rows before the k-step loop
# baseline (speedup 1.0000x reference)
; #define LAS __attribute__((address_space(3)))
; __device__ __forceinline__ void phase_prologue(const Params& P, const Ctx& C, int parts) {
;     ...
;     for (int item = C.blk; item < 192; item += C.nblk) {
;         const int n0 = item * 32, r32 = lane & 31, hi = lane >> 5;
;         LAS float* R = (LAS float*)C.lds;
;         f32x16 acc[5];
; #pragma unroll
;         for (int rt = 0; rt < 5; ++rt) acc[rt] = (f32x16){0.f, 0.f, 0.f, 0.f, 0.f, 0.f, 0.f, 0.f, 0.f, 0.f, 0.f, 0.f, 0.f, 0.f, 0.f, 0.f};
;         const float* wcol = P.in[11] + n0 + r32;
; #pragma unroll 2
;         for (int ks = 0; ks < 8; ++ks) {
;             const int k0 = wave * 128 + ks * 16 + 8 * hi;
;             float wv[8];
; #pragma unroll
;             for (int i = 0; i < 8; ++i) wv[i] = wcol[(size_t)(k0 + i) * 6144];
.LBB0_9:
	s_lshl_b32 s8, s42, 5
	s_ashr_i32 s9, s8, 31
	v_lshl_add_u64 v[132:133], s[8:9], 2, v[128:129]
	s_mov_b32 s9, 0
	v_mov_b32_e32 v64, 0
	v_mov_b32_e32 v65, v123
	v_mov_b32_e32 v66, v123
	v_mov_b32_e32 v67, v123
	v_mov_b32_e32 v68, v123
	v_mov_b32_e32 v69, v123
	v_mov_b32_e32 v70, v123
	v_mov_b32_e32 v71, v123
	v_mov_b32_e32 v72, v123
	v_mov_b32_e32 v73, v123
	v_mov_b32_e32 v74, v123
	v_mov_b32_e32 v75, v123
	v_mov_b32_e32 v76, v123
	v_mov_b32_e32 v77, v123
	v_mov_b32_e32 v78, v123
	v_mov_b32_e32 v79, v123
	v_mov_b32_e32 v48, 0
	v_mov_b32_e32 v49, v123
	v_mov_b32_e32 v50, v123
	v_mov_b32_e32 v51, v123
	v_mov_b32_e32 v52, v123
	v_mov_b32_e32 v53, v123
	v_mov_b32_e32 v54, v123
	v_mov_b32_e32 v55, v123
	v_mov_b32_e32 v56, v123
	v_mov_b32_e32 v57, v123
	v_mov_b32_e32 v58, v123
	v_mov_b32_e32 v59, v123
	v_mov_b32_e32 v60, v123
	v_mov_b32_e32 v61, v123
	v_mov_b32_e32 v62, v123
	v_mov_b32_e32 v63, v123
	v_mov_b32_e32 v32, 0
	v_mov_b32_e32 v33, v123
	v_mov_b32_e32 v34, v123
	v_mov_b32_e32 v35, v123
	v_mov_b32_e32 v36, v123
	v_mov_b32_e32 v37, v123
	v_mov_b32_e32 v38, v123
	v_mov_b32_e32 v39, v123
	v_mov_b32_e32 v40, v123
	v_mov_b32_e32 v41, v123
	v_mov_b32_e32 v42, v123
	v_mov_b32_e32 v43, v123
	v_mov_b32_e32 v44, v123
	v_mov_b32_e32 v45, v123
	v_mov_b32_e32 v46, v123
	v_mov_b32_e32 v47, v123
	v_mov_b32_e32 v16, 0
	v_mov_b32_e32 v17, v123
	v_mov_b32_e32 v18, v123
	v_mov_b32_e32 v19, v123
	v_mov_b32_e32 v20, v123
	v_mov_b32_e32 v21, v123
	v_mov_b32_e32 v22, v123
	v_mov_b32_e32 v23, v123
	v_mov_b32_e32 v24, v123
	v_mov_b32_e32 v25, v123
	v_mov_b32_e32 v26, v123
	v_mov_b32_e32 v27, v123
	v_mov_b32_e32 v28, v123
	v_mov_b32_e32 v29, v123
	v_mov_b32_e32 v30, v123
	v_mov_b32_e32 v31, v123
	v_mov_b32_e32 v0, 0
	v_mov_b32_e32 v1, v123
	v_mov_b32_e32 v2, v123
	v_mov_b32_e32 v3, v123
	v_mov_b32_e32 v4, v123
	v_mov_b32_e32 v5, v123
	v_mov_b32_e32 v6, v123
	v_mov_b32_e32 v7, v123
	v_mov_b32_e32 v8, v123
	v_mov_b32_e32 v9, v123
	v_mov_b32_e32 v10, v123
	v_mov_b32_e32 v11, v123
	v_mov_b32_e32 v12, v123
	v_mov_b32_e32 v13, v123
	v_mov_b32_e32 v14, v123
	v_mov_b32_e32 v15, v123
	v_and_b32_e32 v236, 0xffffff80, v181
	v_add_u32_e32 v236, v236, v134
	v_add_u32_e32 v239, 64, v236
	v_mad_i64_i32 v[236:237], s[30:31], v236, s36, v[132:133]
	v_mad_i64_i32 v[240:241], s[30:31], v239, s36, v[132:133]
	global_load_dword v238, v[236:237], off
	global_load_dword v242, v[240:241], off
